# P3 counter prefetch with the downstream code placement kept (pad to a 64-byte shift)
# speedup vs baseline: 1.0089x; 1.0089x over previous
; __device__ __forceinline__ unsigned xb_ld(unsigned* p)              { return __hip_atomic_load(p, __ATOMIC_RELAXED, __HIP_MEMORY_SCOPE_AGENT); }
; #define XB_SPIN(cond, bar) do { unsigned _sp = 0; while (cond) { __builtin_amdgcn_s_sleep(1); \
;     if ((++_sp & 255u) == 0u) { if (xb_ld(&(bar)[XB_TMO])) break; if (_sp > XB_SPIN_CAP) { atomicAdd(&(bar)[XB_TMO], 1u); break; } } } } while (0)
; __global__ void __launch_bounds__(NTHR, 2) k_main(Args a) {
;     ...
;         if (tid == 0) {
;             int plo = 0, phi = T / 256 - 1;
;             if (nb == 256) { const int r0 = min(max(64 * bid - 128, 0), max(128 * (bid >> 1) - 3, 0)), r1 = max(64 * bid + 63, 128 * (bid >> 1) + 127); plo = r0 >> 8; phi = r1 >> 8; }
;             for (int p = plo; p <= phi; ++p) { unsigned* cw = &((unsigned*)ws)[8192 + 16 * p]; XB_SPIN(xb_ld(cw) < (unsigned)(PS / 256), (unsigned*)ws); }
;             __builtin_amdgcn_fence(__ATOMIC_ACQUIRE, "agent");
;             asm volatile("s_waitcnt vmcnt(0)" ::: "memory");
.LBB0_150:
	s_cmp_gt_i32 s3, s14
	s_cbranch_scc1 .LBB0_166
	s_mov_b32 s5, 0
	v_mov_b32_e32 v1, 0x8000
	v_mov_b32_e32 v2, 0
	s_lshl_b32 s4, s14, 6
	s_add_u32 s6, s90, s4
	s_addc_u32 s7, s91, 0
	global_load_dword v210, v1, s[6:7] sc1
	s_nop 0
	s_nop 0
	s_nop 0
	s_nop 0
	s_nop 0
	s_nop 0
	s_branch .LBB0_154
